# GEMM phase prologues: second batch of stage loads issued before the first wait (vmcnt 2 -> 8), one round trip less per pipeline fill
# baseline (speedup 1.0000x reference)
.LBB0_387:
	s_xor_b64 s[72:73], s[34:35], -1
	s_and_b64 s[12:13], s[44:45], exec
	v_readlane_b32 s12, v252, 2
	v_readlane_b32 s13, v252, 3
	v_readlane_b32 s14, v252, 4
	v_readlane_b32 s15, v252, 5
	s_mov_b32 s65, s67
	s_cselect_b32 s61, s13, s59
	s_cselect_b32 s62, s12, s58
	s_lshl_b32 s66, s0, 15
	s_lshl_b64 s[12:13], s[64:65], 2
	v_readlane_b32 s14, v252, 22
	v_readlane_b32 s15, v252, 23
	s_add_u32 s12, s14, s12
	v_readlane_b32 s17, v252, 7
	s_addc_u32 s13, s15, s13
	s_add_u32 s17, s12, 0x2000
	s_addc_u32 s63, s13, 0
	s_lshl_b64 s[12:13], s[66:67], 2
	v_readlane_b32 s14, v252, 57
	s_add_u32 s12, s14, s12
	v_readlane_b32 s14, v252, 58
	s_addc_u32 s13, s14, s13
	s_add_u32 s68, s12, 0x10000
	s_addc_u32 s69, s13, 0
	s_add_i32 m0, s33, 0x18000
	v_lshl_add_u64 v[6:7], v[6:7], 0, s[70:71]
	s_and_b32 s74, s10, 3
	global_load_lds_dwordx4 v[6:7], off
	v_lshl_add_u64 v[4:5], v[4:5], 0, s[70:71]
	s_add_i32 m0, s33, 0x1a000
	s_add_i32 s75, s33, 0x8000
	s_add_i32 s76, s33, 0xa000
	global_load_lds_dwordx4 v[4:5], off
	v_lshl_add_u64 v[0:1], v[0:1], 0, s[70:71]
	s_mov_b32 m0, s75
	s_add_u32 s12, s42, 0x40080
	global_load_lds_dwordx4 v[0:1], off
	v_lshl_add_u64 v[0:1], v[2:3], 0, s[70:71]
	s_mov_b32 m0, s76
	s_addc_u32 s13, s43, 0
	global_load_lds_dwordx4 v[0:1], off
	s_add_i32 m0, s33, 0x1c000
	v_lshl_add_u64 v[0:1], s[12:13], 0, v[152:153]
	global_load_lds_dwordx4 v[0:1], off
	v_lshl_add_u64 v[0:1], s[12:13], 0, v[166:167]
	s_add_i32 m0, s33, 0x1e000
	v_and_b32_e32 v2, 48, v9
	global_load_lds_dwordx4 v[0:1], off
	v_and_b32_e32 v0, 15, v9
	v_lshl_or_b32 v184, s11, 6, v0
	v_and_b32_e32 v3, 0xfffffc00, v12
	v_lshl_or_b32 v0, v0, 6, v2
	v_lshlrev_b32_e32 v2, 2, v9
	v_lshl_add_u32 v4, s11, 13, v3
	v_and_b32_e32 v2, 32, v2
	v_lshl_add_u32 v3, s74, 12, v3
	v_ashrrev_i32_e32 v1, 1, v9
	v_bitop3_b32 v4, v0, v4, v2 bitop3:0xde
	v_bitop3_b32 v185, v0, v3, v2 bitop3:0xde
	v_lshlrev_b32_e32 v0, 14, v8
	v_and_b32_e32 v1, -8, v1
	v_and_b32_e32 v0, 0xffff8000, v0
	v_lshl_add_u32 v186, s74, 5, v1
	v_lshl_add_u32 v0, v10, 11, v0
	v_and_b32_e32 v1, 1, v8
	v_lshl_or_b32 v0, v1, 6, v0
	v_lshl_add_u32 v168, v11, 1, v0
	v_lshlrev_b32_e32 v0, 14, v13
	v_and_b32_e32 v0, 0xffff8000, v0
	s_waitcnt vmcnt(8)
	s_barrier
	s_waitcnt vmcnt(6)
	v_lshl_add_u32 v0, v14, 11, v0
	v_and_b32_e32 v1, 1, v13
	v_readlane_b32 s16, v252, 6
	v_readlane_b32 s22, v252, 12
	s_cmp_lt_u32 s10, 4
	v_lshl_or_b32 v0, v1, 6, v0
	v_readlane_b32 s8, v254, 23
	s_mov_b32 s16, s64
	s_cselect_b64 s[14:15], -1, 0
	v_cmp_gt_u32_e64 s[38:39], 16, v9
	v_or_b32_e32 v187, 16, v184
	v_or_b32_e32 v188, 32, v184
	v_or_b32_e32 v189, 48, v184
	v_add_u32_e32 v190, 0x80, v184
	v_add_u32_e32 v191, 0x90, v184
	v_add_u32_e32 v192, 0xa0, v184
	v_add_u32_e32 v193, 0xb0, v184
	v_mov_b32_e32 v169, v153
	v_lshl_add_u32 v170, v15, 1, v0
	v_mov_b32_e32 v171, v153
	s_mov_b32 s77, 0
	v_add_u32_e32 v194, 0, v4
	v_readlane_b32 s82, v254, 17
	s_mov_b32 s22, s8
	v_readlane_b32 s18, v252, 8
	v_readlane_b32 s19, v252, 9
	v_readlane_b32 s20, v252, 10
	v_readlane_b32 s21, v252, 11
	v_readlane_b32 s23, v252, 13
	v_readlane_b32 s24, v252, 14
	v_readlane_b32 s25, v252, 15
	v_readlane_b32 s26, v252, 16
	v_readlane_b32 s27, v252, 17
	s_barrier
	v_readlane_b32 s9, v254, 24
	s_branch .LBB0_390

.LBB0_553:
	s_lshl_b64 s[18:19], s[0:1], 18
	v_readlane_b32 s1, v252, 51
	s_add_u32 s1, s1, s18
	v_readlane_b32 s13, v252, 52
	v_and_b32_e32 v15, 15, v14
	s_addc_u32 s31, s13, s19
	v_lshl_or_b32 v168, s12, 6, v15
	v_ashrrev_i32_e32 v17, 6, v14
	s_lshl_b32 s12, s12, 13
	v_lshl_add_u32 v19, v17, 10, s12
	s_lshl_b32 s12, s14, 5
	s_and_b32 s15, s12, 0x60
	s_add_i32 m0, s25, 0x18000
	v_lshl_add_u64 v[6:7], v[6:7], 0, s[70:71]
	s_lshr_b32 s12, s15, 3
	global_load_lds_dwordx4 v[6:7], off
	v_lshl_add_u64 v[4:5], v[4:5], 0, s[70:71]
	s_add_i32 m0, s25, 0x1a000
	s_add_i32 s33, s25, 0x8000
	s_add_i32 s36, s25, 0xa000
	v_add_lshl_u32 v17, s12, v17, 10
	global_load_lds_dwordx4 v[4:5], off
	v_lshl_add_u64 v[0:1], v[0:1], 0, s[70:71]
	s_mov_b32 m0, s33
	s_add_u32 s12, s64, 0x40080
	global_load_lds_dwordx4 v[0:1], off
	v_lshl_add_u64 v[0:1], v[2:3], 0, s[70:71]
	s_mov_b32 m0, s36
	s_addc_u32 s13, s65, 0
	global_load_lds_dwordx4 v[0:1], off
	s_add_i32 m0, s25, 0x1c000
	v_lshl_add_u64 v[0:1], s[12:13], 0, v[152:153]
	global_load_lds_dwordx4 v[0:1], off
	v_lshl_add_u64 v[0:1], s[12:13], 0, v[148:149]
	s_add_i32 m0, s25, 0x1e000
	v_ashrrev_i32_e32 v16, 1, v14
	global_load_lds_dwordx4 v[0:1], off
	v_lshlrev_b32_e32 v0, 14, v8
	v_and_b32_e32 v0, 0xffff8000, v0
	v_lshl_add_u32 v0, v9, 11, v0
	v_and_b32_e32 v1, 1, v8
	v_lshl_or_b32 v0, v1, 6, v0
	v_lshl_add_u32 v150, v10, 1, v0
	v_lshlrev_b32_e32 v0, 14, v11
	v_and_b32_e32 v18, 48, v14
	v_lshlrev_b32_e32 v14, 2, v14
	v_and_b32_e32 v0, 0xffff8000, v0
	v_lshl_or_b32 v15, v15, 6, v18
	v_and_b32_e32 v14, 32, v14
	s_waitcnt vmcnt(8)
	s_barrier
	s_waitcnt vmcnt(6)
	v_lshl_add_u32 v0, v12, 11, v0
	v_and_b32_e32 v1, 1, v11
	v_and_b32_e32 v16, -8, v16
	v_bitop3_b32 v18, v15, v19, v14 bitop3:0xde
	s_cmp_lt_u32 s14, 4
	v_lshl_or_b32 v0, v1, 6, v0
	v_bitop3_b32 v169, v15, v17, v14 bitop3:0xde
	s_cselect_b64 s[12:13], -1, 0
	v_add_u32_e32 v170, s15, v16
	v_mov_b32_e32 v151, v153
	v_lshl_add_u32 v162, v13, 1, v0
	v_mov_b32_e32 v163, v153
	s_mov_b32 s22, 0
	v_add_u32_e32 v171, 0, v18
	s_barrier
	s_branch .LBB0_556

.LBB0_625:
	s_mov_b32 s65, s67
	s_lshl_b32 s66, s0, 15
	s_lshl_b64 s[4:5], s[64:65], 2
	v_readlane_b32 s16, v252, 22
	v_readlane_b32 s17, v252, 23
	s_add_u32 s0, s16, s4
	s_addc_u32 s4, s17, s5
	s_add_u32 s88, s0, 0x32000
	s_addc_u32 s5, s4, 0
	s_lshl_b64 s[16:17], s[66:67], 2
	v_readlane_b32 s0, v252, 57
	s_add_u32 s0, s0, s16
	v_readlane_b32 s4, v252, 58
	s_addc_u32 s4, s4, s17
	s_add_u32 s66, s0, 0x20000
	s_addc_u32 s4, s4, 0
	s_add_i32 m0, s60, 0x18000
	v_lshl_add_u64 v[6:7], v[6:7], 0, s[70:71]
	s_and_b32 s16, s1, 3
	s_lshl_b32 s68, s14, 6
	v_and_b32_e32 v15, 0xfffffc00, v15
	global_load_lds_dwordx4 v[6:7], off
	v_lshl_add_u64 v[4:5], v[4:5], 0, s[70:71]
	s_add_i32 m0, s60, 0x1a000
	s_add_i32 s69, s60, 0x8000
	s_add_i32 s92, s60, 0xa000
	v_lshl_add_u32 v18, s14, 13, v15
	global_load_lds_dwordx4 v[4:5], off
	v_lshl_add_u64 v[0:1], v[0:1], 0, s[70:71]
	s_mov_b32 m0, s69
	s_add_u32 s14, s12, 0x100080
	global_load_lds_dwordx4 v[0:1], off
	v_lshl_add_u64 v[0:1], v[2:3], 0, s[70:71]
	s_mov_b32 m0, s92
	s_addc_u32 s15, s13, 0
	global_load_lds_dwordx4 v[0:1], off
	s_add_i32 m0, s60, 0x1c000
	v_lshl_add_u64 v[0:1], s[14:15], 0, v[152:153]
	global_load_lds_dwordx4 v[0:1], off
	v_lshl_add_u64 v[0:1], s[14:15], 0, v[148:149]
	s_add_i32 m0, s60, 0x1e000
	v_and_b32_e32 v247, 15, v8
	global_load_lds_dwordx4 v[0:1], off
	v_lshlrev_b32_e32 v0, 16, v9
	v_and_b32_e32 v0, 0xfffe0000, v0
	v_lshl_add_u32 v0, v10, 13, v0
	v_and_b32_e32 v1, 1, v9
	v_lshl_or_b32 v0, v1, 6, v0
	v_lshl_add_u32 v150, v11, 1, v0
	v_lshlrev_b32_e32 v0, 16, v12
	v_and_b32_e32 v17, 48, v8
	v_lshlrev_b32_e32 v19, 2, v8
	v_and_b32_e32 v0, 0xfffe0000, v0
	v_ashrrev_i32_e32 v16, 1, v8
	v_lshl_or_b32 v17, v247, 6, v17
	v_and_b32_e32 v19, 32, v19
	s_waitcnt vmcnt(8)
	s_barrier
	s_waitcnt vmcnt(6)
	v_lshl_add_u32 v0, v13, 13, v0
	v_and_b32_e32 v1, 1, v12
	v_readlane_b32 s8, v254, 27
	v_and_b32_e32 v16, -8, v16
	v_bitop3_b32 v18, v17, v18, v19 bitop3:0xde
	v_lshl_add_u32 v15, s16, 12, v15
	s_cmp_lt_u32 s1, 4
	v_lshl_or_b32 v0, v1, 6, v0
	v_readlane_b32 s9, v254, 28
	v_or_b32_e32 v248, s68, v247
	v_bitop3_b32 v249, v17, v15, v19 bitop3:0xde
	s_cselect_b64 s[0:1], -1, 0
	v_lshl_add_u32 v250, s16, 5, v16
	v_cmp_gt_u32_e64 s[38:39], 16, v8
	v_mov_b32_e32 v151, v153
	v_lshl_add_u32 v162, v14, 1, v0
	v_mov_b32_e32 v163, v153
	s_mov_b32 s90, 0
	v_add_u32_e32 v251, 0, v18
	s_lshl_b32 s91, s16, 2
	v_readlane_b32 s76, v254, 20
	s_mov_b32 s77, s8
	v_readlane_b32 s8, v254, 10
	v_readlane_b32 s9, v254, 11
	s_barrier
	s_branch .LBB0_628

.LBB0_784:
	s_lshl_b32 s35, s39, 6
	v_ashrrev_i32_e32 v16, 6, v14
	s_lshl_b32 s39, s39, 13
	v_lshl_add_u32 v18, v16, 10, s39
	s_lshl_b32 s39, s38, 5
	s_and_b32 s39, s39, 0x60
	s_add_i32 m0, s11, 0x18000
	v_lshl_add_u64 v[6:7], v[6:7], 0, s[16:17]
	s_lshr_b32 s42, s39, 3
	global_load_lds_dwordx4 v[6:7], off
	v_lshl_add_u64 v[4:5], v[4:5], 0, s[16:17]
	s_add_i32 m0, s11, 0x1a000
	s_add_i32 s46, s11, 0x8000
	s_add_i32 s47, s11, 0xa000
	v_add_lshl_u32 v16, s42, v16, 10
	global_load_lds_dwordx4 v[4:5], off
	v_lshl_add_u64 v[0:1], v[0:1], 0, s[16:17]
	s_mov_b32 m0, s46
	s_add_u32 s42, s30, 0x40080
	global_load_lds_dwordx4 v[0:1], off
	v_lshl_add_u64 v[0:1], v[2:3], 0, s[16:17]
	s_mov_b32 m0, s47
	s_addc_u32 s43, s31, 0
	global_load_lds_dwordx4 v[0:1], off
	s_add_i32 m0, s11, 0x1c000
	v_lshl_add_u64 v[0:1], s[42:43], 0, v[148:149]
	global_load_lds_dwordx4 v[0:1], off
	v_lshl_add_u64 v[0:1], s[42:43], 0, v[152:153]
	s_add_i32 m0, s11, 0x1e000
	v_ashrrev_i32_e32 v15, 1, v14
	global_load_lds_dwordx4 v[0:1], off
	v_and_b32_e32 v15, -8, v15
	v_add_u32_e32 v170, s39, v15
	s_cmp_lt_u32 s38, 4
	v_and_b32_e32 v0, 56, v170
	v_readlane_b32 s38, v254, 33
	v_lshlrev_b32_e32 v0, 1, v0
	v_mov_b32_e32 v1, v64
	v_readlane_b32 s39, v254, 34
	v_and_b32_e32 v65, 15, v14
	v_and_b32_e32 v17, 48, v14
	v_lshl_add_u64 v[154:155], s[38:39], 0, v[0:1]
	v_lshlrev_b32_e32 v0, 14, v8
	v_and_b32_e32 v0, 0xffff8000, v0
	v_lshl_add_u32 v0, v9, 11, v0
	v_and_b32_e32 v1, 1, v8
	v_lshl_or_b32 v0, v1, 6, v0
	v_lshl_add_u32 v156, v10, 1, v0
	v_lshlrev_b32_e32 v0, 14, v11
	v_lshlrev_b32_e32 v14, 2, v14
	v_and_b32_e32 v0, 0xffff8000, v0
	v_lshl_or_b32 v17, v65, 6, v17
	v_and_b32_e32 v14, 32, v14
	s_waitcnt vmcnt(8)
	s_barrier
	s_waitcnt vmcnt(6)
	v_lshl_add_u32 v0, v12, 11, v0
	v_and_b32_e32 v1, 1, v11
	v_bitop3_b32 v18, v17, v18, v14 bitop3:0xde
	v_lshl_or_b32 v0, v1, 6, v0
	v_readlane_b32 s38, v254, 54
	v_bitop3_b32 v167, v17, v16, v14 bitop3:0xde
	s_cselect_b64 s[42:43], -1, 0
	v_mov_b32_e32 v157, v64
	v_lshl_add_u32 v158, v13, 1, v0
	v_mov_b32_e32 v159, v64
	s_mov_b32 s72, 0
	v_add_u32_e32 v171, 0, v18
	v_readlane_b32 s70, v254, 50
	s_mov_b32 s71, s38
	s_barrier
	v_readlane_b32 s39, v254, 55
	s_branch .LBB0_787

.LBB0_887:
	s_lshl_b32 s35, s39, 6
	v_ashrrev_i32_e32 v16, 6, v14
	s_lshl_b32 s39, s39, 13
	v_lshl_add_u32 v18, v16, 10, s39
	s_lshl_b32 s39, s38, 5
	s_and_b32 s39, s39, 0x60
	s_lshr_b32 s42, s39, 3
	v_add_lshl_u32 v16, s42, v16, 10
	v_readlane_b32 s42, v254, 21
	s_mul_i32 s42, s42, 0x30000
	v_readlane_b32 s43, v252, 53
	s_add_u32 s46, s43, s42
	v_readlane_b32 s42, v252, 54
	s_addc_u32 s47, s42, 0
	s_add_i32 m0, s11, 0x18000
	v_lshl_add_u64 v[6:7], v[6:7], 0, s[16:17]
	global_load_lds_dwordx4 v[6:7], off
	v_lshl_add_u64 v[4:5], v[4:5], 0, s[16:17]
	s_add_i32 m0, s11, 0x1a000
	s_add_i32 s61, s11, 0x8000
	s_add_i32 s70, s11, 0xa000
	global_load_lds_dwordx4 v[4:5], off
	v_lshl_add_u64 v[0:1], v[0:1], 0, s[16:17]
	s_mov_b32 m0, s61
	s_add_u32 s42, s30, 0x40080
	global_load_lds_dwordx4 v[0:1], off
	v_lshl_add_u64 v[0:1], v[2:3], 0, s[16:17]
	s_mov_b32 m0, s70
	s_addc_u32 s43, s31, 0
	global_load_lds_dwordx4 v[0:1], off
	s_add_i32 m0, s11, 0x1c000
	v_lshl_add_u64 v[0:1], s[42:43], 0, v[148:149]
	global_load_lds_dwordx4 v[0:1], off
	v_lshl_add_u64 v[0:1], s[42:43], 0, v[152:153]
	s_add_i32 m0, s11, 0x1e000
	v_ashrrev_i32_e32 v15, 1, v14
	global_load_lds_dwordx4 v[0:1], off
	v_and_b32_e32 v15, -8, v15
	v_add_u32_e32 v170, s39, v15
	s_cmp_lt_u32 s38, 4
	v_and_b32_e32 v0, 56, v170
	v_readlane_b32 s38, v253, 14
	v_lshlrev_b32_e32 v0, 1, v0
	v_mov_b32_e32 v1, v64
	v_readlane_b32 s39, v253, 15
	v_and_b32_e32 v65, 15, v14
	v_and_b32_e32 v17, 48, v14
	v_lshl_add_u64 v[154:155], s[38:39], 0, v[0:1]
	v_lshlrev_b32_e32 v0, 14, v8
	v_and_b32_e32 v0, 0xffff8000, v0
	v_lshl_add_u32 v0, v9, 11, v0
	v_and_b32_e32 v1, 1, v8
	v_lshl_or_b32 v0, v1, 6, v0
	v_lshl_add_u32 v156, v10, 1, v0
	v_lshlrev_b32_e32 v0, 14, v11
	v_lshlrev_b32_e32 v14, 2, v14
	v_and_b32_e32 v0, 0xffff8000, v0
	v_lshl_or_b32 v17, v65, 6, v17
	v_and_b32_e32 v14, 32, v14
	s_waitcnt vmcnt(8)
	s_barrier
	s_waitcnt vmcnt(6)
	v_lshl_add_u32 v0, v12, 11, v0
	v_and_b32_e32 v1, 1, v11
	v_bitop3_b32 v18, v17, v18, v14 bitop3:0xde
	v_lshl_or_b32 v0, v1, 6, v0
	v_readlane_b32 s38, v253, 6
	v_bitop3_b32 v167, v17, v16, v14 bitop3:0xde
	s_cselect_b64 s[42:43], -1, 0
	v_mov_b32_e32 v157, v64
	v_lshl_add_u32 v158, v13, 1, v0
	v_mov_b32_e32 v159, v64
	s_mov_b32 s74, 0
	v_add_u32_e32 v171, 0, v18
	v_readlane_b32 s72, v253, 10
	s_mov_b32 s73, s38
	s_barrier
	v_readlane_b32 s39, v253, 7
	s_branch .LBB0_890

.LBB0_1240:
	v_readlane_b32 s13, v253, 8
	s_mul_i32 s44, s13, 0x18000
	s_mov_b32 s45, s60
	s_lshl_b32 s40, s13, 15
	s_lshl_b64 s[44:45], s[44:45], 2
	v_readlane_b32 s48, v252, 22
	v_readlane_b32 s49, v252, 23
	s_add_u32 s13, s48, s44
	s_addc_u32 s19, s49, s45
	s_add_u32 s13, s13, 0x2000
	s_mov_b32 s41, s60
	s_addc_u32 s92, s19, 0
	s_lshl_b64 s[40:41], s[40:41], 2
	v_readlane_b32 s19, v252, 57
	s_add_u32 s19, s19, s40
	v_readlane_b32 s39, v252, 58
	s_addc_u32 s39, s39, s41
	s_add_u32 s93, s19, 0x10000
	s_addc_u32 s46, s39, 0
	v_and_b32_e32 v15, 0xfffffc00, v15
	s_add_i32 m0, s0, 0x18000
	v_lshl_add_u64 v[6:7], v[6:7], 0, s[16:17]
	s_and_b32 s48, s38, 3
	s_lshl_b32 s19, s4, 6
	v_lshl_add_u32 v18, s4, 13, v15
	global_load_lds_dwordx4 v[6:7], off
	v_lshl_add_u64 v[4:5], v[4:5], 0, s[16:17]
	s_add_i32 m0, s0, 0x1a000
	s_add_i32 s4, s0, 0x8000
	s_add_i32 s90, s0, 0xa000
	global_load_lds_dwordx4 v[4:5], off
	v_lshl_add_u64 v[0:1], v[0:1], 0, s[16:17]
	s_mov_b32 m0, s4
	s_add_u32 s40, s30, 0x40080
	global_load_lds_dwordx4 v[0:1], off
	v_lshl_add_u64 v[0:1], v[2:3], 0, s[16:17]
	s_mov_b32 m0, s90
	s_addc_u32 s41, s31, 0
	global_load_lds_dwordx4 v[0:1], off
	s_add_i32 m0, s0, 0x1c000
	v_lshl_add_u64 v[0:1], s[40:41], 0, v[152:153]
	global_load_lds_dwordx4 v[0:1], off
	v_lshl_add_u64 v[0:1], s[40:41], 0, v[156:157]
	s_add_i32 m0, s0, 0x1e000
	v_and_b32_e32 v65, 15, v8
	global_load_lds_dwordx4 v[0:1], off
	v_lshlrev_b32_e32 v0, 14, v9
	v_and_b32_e32 v0, 0xffff8000, v0
	v_lshl_add_u32 v0, v10, 11, v0
	v_and_b32_e32 v1, 1, v9
	v_lshl_or_b32 v0, v1, 6, v0
	v_lshl_add_u32 v158, v11, 1, v0
	v_lshlrev_b32_e32 v0, 14, v12
	v_and_b32_e32 v17, 48, v8
	v_lshlrev_b32_e32 v19, 2, v8
	v_and_b32_e32 v0, 0xffff8000, v0
	v_ashrrev_i32_e32 v16, 1, v8
	v_lshl_or_b32 v17, v65, 6, v17
	v_and_b32_e32 v19, 32, v19
	s_waitcnt vmcnt(8)
	s_barrier
	s_waitcnt vmcnt(6)
	v_lshl_add_u32 v0, v13, 11, v0
	v_and_b32_e32 v1, 1, v12
	v_and_b32_e32 v16, -8, v16
	v_bitop3_b32 v18, v17, v18, v19 bitop3:0xde
	v_lshl_add_u32 v15, s48, 12, v15
	s_cmp_lt_u32 s38, 4
	v_lshl_or_b32 v0, v1, 6, v0
	v_readlane_b32 s40, v252, 28
	v_or_b32_e32 v222, s19, v65
	v_bitop3_b32 v223, v17, v15, v19 bitop3:0xde
	s_cselect_b64 s[44:45], -1, 0
	v_lshl_add_u32 v224, s48, 5, v16
	v_cmp_gt_u32_e64 s[38:39], 16, v8
	v_mov_b32_e32 v159, v64
	v_lshl_add_u32 v160, v14, 1, v0
	v_mov_b32_e32 v161, v64
	s_mov_b32 s91, 0
	v_add_u32_e32 v225, 0, v18
	s_lshl_b32 s76, s48, 2
	v_readlane_b32 s77, v253, 5
	s_mov_b32 s82, s40
	s_barrier
	v_readlane_b32 s41, v252, 29
	s_branch .LBB0_1243

.LBB0_1378:
	v_readlane_b32 s29, v253, 8
	s_lshl_b32 s44, s29, 16
	s_mov_b32 s45, s60
	s_lshl_b64 s[44:45], s[44:45], 2
	v_readlane_b32 s29, v252, 51
	s_add_u32 s35, s29, s44
	v_readlane_b32 s29, v252, 52
	s_addc_u32 s46, s29, s45
	v_ashrrev_i32_e32 v17, 6, v14
	s_lshl_b32 s29, s38, 13
	v_lshl_add_u32 v19, v17, 10, s29
	s_lshl_b32 s29, s42, 5
	v_and_b32_e32 v15, 15, v14
	s_and_b32 s29, s29, 0x60
	s_add_i32 m0, s11, 0x18000
	v_lshl_add_u64 v[6:7], v[6:7], 0, s[16:17]
	v_lshl_or_b32 v65, s38, 6, v15
	s_lshr_b32 s38, s29, 3
	global_load_lds_dwordx4 v[6:7], off
	v_lshl_add_u64 v[4:5], v[4:5], 0, s[16:17]
	s_add_i32 m0, s11, 0x1a000
	s_add_i32 s47, s11, 0x8000
	s_add_i32 s61, s11, 0xa000
	v_add_lshl_u32 v17, s38, v17, 10
	global_load_lds_dwordx4 v[4:5], off
	v_lshl_add_u64 v[0:1], v[0:1], 0, s[16:17]
	s_mov_b32 m0, s47
	s_add_u32 s38, s68, 0x40080
	global_load_lds_dwordx4 v[0:1], off
	v_lshl_add_u64 v[0:1], v[2:3], 0, s[16:17]
	s_mov_b32 m0, s61
	s_addc_u32 s39, s69, 0
	global_load_lds_dwordx4 v[0:1], off
	s_add_i32 m0, s11, 0x1c000
	v_lshl_add_u64 v[0:1], s[38:39], 0, v[148:149]
	global_load_lds_dwordx4 v[0:1], off
	v_lshl_add_u64 v[0:1], s[38:39], 0, v[152:153]
	s_add_i32 m0, s11, 0x1e000
	v_ashrrev_i32_e32 v16, 1, v14
	global_load_lds_dwordx4 v[0:1], off
	v_lshlrev_b32_e32 v0, 14, v8
	v_and_b32_e32 v0, 0xffff8000, v0
	v_lshl_add_u32 v0, v9, 11, v0
	v_and_b32_e32 v1, 1, v8
	v_lshl_or_b32 v0, v1, 6, v0
	v_lshl_add_u32 v154, v10, 1, v0
	v_lshlrev_b32_e32 v0, 14, v11
	v_and_b32_e32 v18, 48, v14
	v_lshlrev_b32_e32 v14, 2, v14
	v_and_b32_e32 v0, 0xffff8000, v0
	v_lshl_or_b32 v15, v15, 6, v18
	v_and_b32_e32 v14, 32, v14
	s_waitcnt vmcnt(8)
	s_barrier
	s_waitcnt vmcnt(6)
	v_lshl_add_u32 v0, v12, 11, v0
	v_and_b32_e32 v1, 1, v11
	v_and_b32_e32 v16, -8, v16
	v_bitop3_b32 v18, v15, v19, v14 bitop3:0xde
	s_cmp_lt_u32 s42, 4
	v_lshl_or_b32 v0, v1, 6, v0
	v_bitop3_b32 v162, v15, v17, v14 bitop3:0xde
	s_cselect_b64 s[42:43], -1, 0
	v_add_u32_e32 v163, s29, v16
	v_mov_b32_e32 v155, v64
	v_lshl_add_u32 v156, v13, 1, v0
	v_mov_b32_e32 v157, v64
	s_mov_b32 s29, 0
	v_add_u32_e32 v164, 0, v18
	s_barrier
	s_branch .LBB0_1381

.LBB0_1451:
	s_add_i32 m0, s11, 0x18000
	v_lshl_add_u64 v[6:7], v[6:7], 0, s[16:17]
	s_and_b32 s44, s34, 3
	global_load_lds_dwordx4 v[6:7], off
	v_lshl_add_u64 v[4:5], v[4:5], 0, s[16:17]
	s_add_i32 m0, s11, 0x1a000
	s_add_i32 s76, s11, 0x8000
	s_add_i32 s77, s11, 0xa000
	global_load_lds_dwordx4 v[4:5], off
	v_lshl_add_u64 v[0:1], v[0:1], 0, s[16:17]
	s_mov_b32 m0, s76
	s_add_u32 s38, s30, 0x100080
	global_load_lds_dwordx4 v[0:1], off
	v_lshl_add_u64 v[0:1], v[2:3], 0, s[16:17]
	s_mov_b32 m0, s77
	s_addc_u32 s39, s31, 0
	global_load_lds_dwordx4 v[0:1], off
	s_add_i32 m0, s11, 0x1c000
	v_lshl_add_u64 v[0:1], s[38:39], 0, v[192:193]
	global_load_lds_dwordx4 v[0:1], off
	v_lshl_add_u64 v[0:1], s[38:39], 0, v[196:197]
	s_add_i32 m0, s11, 0x1e000
	v_and_b32_e32 v16, 15, v10
	global_load_lds_dwordx4 v[0:1], off
	v_and_b32_e32 v15, 0xfffffc00, v15
	s_cmp_lt_u32 s34, 4
	v_lshl_or_b32 v65, s35, 6, v16
	v_lshl_add_u32 v19, s35, 13, v15
	s_cselect_b64 s[64:65], -1, 0
	s_lshl_b32 s35, s35, 10
	s_lshl_b32 s40, s34, 5
	s_cmp_eq_u32 s34, 0
	s_cselect_b64 s[66:67], -1, 0
	s_lshl_b32 s34, s44, 2
	s_add_i32 s34, s34, 0
	v_and_or_b32 v1, v10, 31, s40
	s_add_i32 s34, s34, s35
	v_readlane_b32 s35, v255, 15
	v_lshlrev_b32_e32 v2, 4, v1
	v_add_u32_e32 v248, s27, v1
	v_lshl_add_u32 v249, v1, 2, s35
	v_lshlrev_b32_e32 v1, 16, v8
	v_and_b32_e32 v1, 0xfffe0000, v1
	v_lshl_add_u32 v1, v9, 13, v1
	v_and_b32_e32 v3, 1, v8
	v_lshl_or_b32 v1, v3, 6, v1
	v_lshl_add_u32 v198, v11, 1, v1
	v_lshlrev_b32_e32 v1, 16, v12
	v_and_b32_e32 v18, 48, v10
	v_lshlrev_b32_e32 v20, 2, v65
	v_and_b32_e32 v1, 0xfffe0000, v1
	v_and_b32_e32 v21, 32, v20
	v_lshl_or_b32 v18, v16, 6, v18
	v_lshl_add_u32 v1, v13, 13, v1
	v_and_b32_e32 v3, 1, v12
	v_ashrrev_i32_e32 v17, 1, v10
	v_bitop3_b32 v19, v18, v19, v21 bitop3:0xde
	v_lshlrev_b32_e32 v21, 2, v10
	s_waitcnt vmcnt(8)
	s_barrier
	s_waitcnt vmcnt(6)
	v_lshlrev_b32_e32 v0, 4, v16
	s_add_i32 s34, s34, 0x20000
	v_lshl_or_b32 v1, v3, 6, v1
	v_and_b32_e32 v17, -8, v17
	v_lshl_add_u32 v15, s44, 12, v15
	v_and_b32_e32 v21, 32, v21
	v_lshl_add_u32 v200, v14, 1, v1
	v_add_u32_e32 v1, 0, v2
	v_add_u32_e32 v237, s34, v0
	v_readlane_b32 s34, v253, 5
	v_bitop3_b32 v246, v18, v15, v21 bitop3:0xde
	v_lshl_add_u32 v247, s44, 5, v17
	v_cmp_gt_u32_e64 s[38:39], 16, v10
	v_cmp_gt_i32_e64 s[40:41], 32, v10
	s_mov_b32 s90, 0
	v_cmp_eq_u32_e64 s[42:43], 0, v10
	v_add_u32_e32 v250, s35, v20
	v_mov_b32_e32 v199, v64
	v_mov_b32_e32 v201, v64
	v_add_u32_e32 v251, 0, v19
	v_add_u32_e32 v238, 0x20000, v1
	s_mov_b32 s46, s34
	v_readlane_b32 s34, v252, 28
	s_barrier
	v_readlane_b32 s35, v252, 29
	s_branch .LBB0_1454

.LBB0_1522:
	v_mov_b32_e32 v153, v64
	v_lshl_add_u64 v[8:9], s[30:31], 0, v[152:153]
	v_mov_b32_e32 v157, v64
	v_lshl_add_u64 v[10:11], s[30:31], 0, v[156:157]
	v_mov_b32_e32 v151, v64
	v_and_b32_e32 v7, 0xfffffc00, v7
	s_add_i32 m0, s1, 0x18000
	v_lshl_add_u64 v[8:9], v[8:9], 0, s[16:17]
	v_lshl_add_u64 v[12:13], s[28:29], 0, v[150:151]
	v_mov_b32_e32 v155, v64
	s_and_b32 s46, s38, 3
	s_lshl_b32 s19, s4, 6
	v_lshl_add_u32 v18, s4, 13, v7
	global_load_lds_dwordx4 v[8:9], off
	v_lshl_add_u64 v[8:9], v[10:11], 0, s[16:17]
	s_add_i32 m0, s1, 0x1a000
	s_add_i32 s4, s1, 0x8000
	s_add_i32 s90, s1, 0xa000
	v_lshl_add_u64 v[14:15], s[28:29], 0, v[154:155]
	global_load_lds_dwordx4 v[8:9], off
	v_lshl_add_u64 v[8:9], v[12:13], 0, s[16:17]
	s_mov_b32 m0, s4
	s_add_u32 s40, s30, 0x100080
	global_load_lds_dwordx4 v[8:9], off
	v_lshl_add_u64 v[8:9], v[14:15], 0, s[16:17]
	s_mov_b32 m0, s90
	s_addc_u32 s41, s31, 0
	global_load_lds_dwordx4 v[8:9], off
	s_add_i32 m0, s1, 0x1c000
	v_lshl_add_u64 v[8:9], s[40:41], 0, v[152:153]
	global_load_lds_dwordx4 v[8:9], off
	v_lshl_add_u64 v[8:9], s[40:41], 0, v[156:157]
	s_add_i32 m0, s1, 0x1e000
	v_and_b32_e32 v65, 15, v0
	global_load_lds_dwordx4 v[8:9], off
	v_ashrrev_i32_e32 v16, 1, v0
	v_and_b32_e32 v17, 48, v0
	v_lshlrev_b32_e32 v19, 2, v0
	s_cmp_lt_u32 s38, 4
	v_cmp_gt_u32_e64 s[38:39], 16, v0
	v_lshlrev_b32_e32 v0, 16, v1
	v_and_b32_e32 v0, 0xfffe0000, v0
	v_lshl_add_u32 v0, v2, 13, v0
	v_and_b32_e32 v1, 1, v1
	v_lshl_or_b32 v0, v1, 6, v0
	v_lshl_add_u32 v158, v3, 1, v0
	v_lshlrev_b32_e32 v0, 16, v4
	v_and_b32_e32 v0, 0xfffe0000, v0
	v_lshl_or_b32 v17, v65, 6, v17
	v_and_b32_e32 v19, 32, v19
	s_waitcnt vmcnt(8)
	s_barrier
	s_waitcnt vmcnt(6)
	v_lshl_add_u32 v0, v5, 13, v0
	v_and_b32_e32 v1, 1, v4
	v_and_b32_e32 v16, -8, v16
	v_bitop3_b32 v18, v17, v18, v19 bitop3:0xde
	v_lshl_add_u32 v7, s46, 12, v7
	v_lshl_or_b32 v0, v1, 6, v0
	v_readlane_b32 s40, v252, 28
	v_or_b32_e32 v222, s19, v65
	v_bitop3_b32 v223, v17, v7, v19 bitop3:0xde
	s_cselect_b64 s[44:45], -1, 0
	v_lshl_add_u32 v224, s46, 5, v16
	v_mov_b32_e32 v159, v64
	v_lshl_add_u32 v160, v6, 1, v0
	v_mov_b32_e32 v161, v64
	s_mov_b32 s91, 0
	v_add_u32_e32 v225, 0, v18
	s_lshl_b32 s76, s46, 2
	v_readlane_b32 s77, v253, 5
	s_mov_b32 s74, s40
	s_barrier
	v_readlane_b32 s41, v252, 29
	s_branch .LBB0_1525
